# phase 3: blocks paired with an mLSTM-chain block no longer sleep until the chain ends; the chain waves run at s_setprio 3 instead
# speedup vs baseline: 1.0058x; 1.0058x over previous
.LBB0_143:
	s_or_b64 exec, exec, s[6:7]
	v_readlane_b32 s0, v248, 31
	s_cmp_eq_u32 s0, 3
	v_cmp_eq_u32_e64 s[0:1], 0, v200
	s_cselect_b64 s[4:5], -1, 0
	s_mov_b64 s[44:45], -1
	v_writelane_b32 v248, s0, 34
	s_nop 1
	v_writelane_b32 v248, s1, 35
	v_readlane_b32 s0, v251, 17
	v_readlane_b32 s1, v251, 18
	s_and_b64 s[0:1], s[0:1], s[4:5]
	s_andn2_b64 vcc, exec, s[0:1]
	s_mov_b64 s[0:1], -1
	s_cbranch_vccz .LBB0_149
	s_load_dword s1, s[54:55], 0x0
	v_readlane_b32 s8, v249, 7
	v_readlane_b32 s9, v249, 8
	s_mov_b32 s2, s8
	s_waitcnt lgkmcnt(0)
	s_lshr_b32 s0, s1, 1
	s_cmp_gt_u32 s1, 63
	s_cselect_b64 s[6:7], -1, 0
	s_cmp_ge_i32 s8, s0
	s_cselect_b64 s[8:9], -1, 0
	s_and_b64 s[6:7], s[6:7], s[8:9]
	s_and_b64 s[4:5], s[4:5], s[6:7]
	s_add_i32 s1, s0, 32
	s_cmp_lt_u32 s2, s1
	s_cselect_b64 s[6:7], -1, 0
	s_and_b64 s[4:5], s[4:5], s[6:7]
	s_andn2_b64 vcc, exec, s[4:5]
	s_branch .LBB0_148
	s_mov_b64 s[4:5], exec
	v_readlane_b32 s6, v248, 34
	v_readlane_b32 s7, v248, 35
	s_and_b64 s[6:7], s[4:5], s[6:7]
	s_mov_b64 exec, s[6:7]
	s_cbranch_execz .LBB0_147
	v_readlane_b32 s6, v249, 7
	s_sub_i32 s2, s6, s0
	s_lshl_b64 s[0:1], s[2:3], 2
	v_readlane_b32 s7, v249, 8
	s_add_u32 s6, s92, s0
	s_addc_u32 s7, s93, s1
	s_nop 2
	global_load_dword v0, v197, s[6:7] offset:128 sc1
	s_waitcnt vmcnt(0)
	v_cmp_ne_u32_e32 vcc, 0, v0
	s_cbranch_vccz .LBB0_601

.LBB0_149:
	s_andn2_b64 vcc, exec, s[0:1]
	s_cbranch_vccnz .LBB0_172
	s_setprio 3
	v_mov_b32_e32 v0, v200
	s_waitcnt vmcnt(0)
	v_lshl_add_u32 v117, v0, 2, 0
	v_cmp_gt_i32_e64 s[42:43], 64, v0
	ds_write_b32 v117, v197 offset:54528
	s_and_saveexec_b64 s[0:1], s[42:43]
	ds_write_b32 v117, v197 offset:55552
	s_or_b64 exec, exec, s[0:1]
	v_ashrrev_i32_e32 v18, 2, v0
	v_and_b32_e32 v14, -4, v18
	v_readlane_b32 s4, v250, 53
	v_ashrrev_i32_e32 v15, 31, v14
	v_readlane_b32 s8, v250, 57
	v_readlane_b32 s9, v250, 58
	v_lshl_add_u64 v[2:3], v[14:15], 0, s[94:95]
	s_movk_i32 s2, 0x2800
	v_mov_b64_e32 v[4:5], s[8:9]
	v_mad_u64_u32 v[4:5], s[0:1], v2, s2, v[4:5]
	v_readlane_b32 s0, v251, 19
	v_mad_i32_i24 v5, v3, s2, v5
	s_lshl_b32 s2, s0, 1
	v_lshl_add_u64 v[2:3], v[4:5], 0, s[2:3]
	v_lshlrev_b32_e32 v4, 4, v0
	v_and_b32_e32 v196, 0xf0, v4
	v_lshl_add_u64 v[16:17], v[2:3], 0, v[196:197]
	s_mov_b64 s[0:1], 0x1400
	v_lshl_add_u64 v[112:113], v[16:17], 0, s[0:1]
	s_movk_i32 s0, 0x1000
	v_add_co_u32_e32 v2, vcc, s0, v16
	v_add_u32_e32 v15, 0, v196
	s_nop 0
	v_addc_co_u32_e32 v3, vcc, 0, v17, vcc
	global_load_dwordx4 v[2:5], v[2:3], off offset:1024
	s_nop 0
	global_load_dwordx4 v[6:9], v[112:113], off offset:1024
	s_waitcnt lgkmcnt(0)
	global_load_dwordx4 v[10:13], v[112:113], off offset:2048
	v_mul_lo_u32 v14, v14, s48
	v_add_u32_e32 v119, v15, v14
	s_movk_i32 s0, 0x3000
	v_or_b32_e32 v14, 3, v18
	v_mul_lo_u32 v14, v14, s48
	v_ashrrev_i32_e32 v1, 31, v0
	v_add_u32_e32 v121, v15, v14
	v_lshl_add_u64 v[114:115], v[0:1], 2, s[96:97]
	v_readlane_b32 s5, v250, 54
	v_readlane_b32 s6, v250, 55
	v_readlane_b32 s7, v250, 56
	v_readlane_b32 s10, v250, 59
	v_readlane_b32 s11, v250, 60
	v_readlane_b32 s12, v250, 61
	v_readlane_b32 s13, v250, 62
	v_readlane_b32 s14, v250, 63
	v_readlane_b32 s15, v249, 0
	v_readlane_b32 s16, v249, 1
	v_readlane_b32 s17, v249, 2
	v_readlane_b32 s18, v249, 3
	v_readlane_b32 s19, v249, 4
	s_waitcnt vmcnt(0)
	ds_write_b128 v119, v[2:5]
	ds_write_b128 v119, v[6:9] offset:17408
	ds_write_b128 v119, v[10:13] offset:34816
	v_add_co_u32_e32 v2, vcc, s0, v16
	s_movk_i32 s0, 0x6000
	s_nop 0
	v_addc_co_u32_e32 v3, vcc, 0, v17, vcc
	v_add_co_u32_e32 v10, vcc, s33, v16
	global_load_dwordx4 v[2:5], v[2:3], off offset:3072
	s_nop 0
	v_addc_co_u32_e32 v11, vcc, 0, v17, vcc
	global_load_dwordx4 v[6:9], v[10:11], off
	s_nop 0
	global_load_dwordx4 v[10:13], v[10:11], off offset:1024
	s_waitcnt vmcnt(2)
	ds_write_b128 v119, v[2:5] offset:272
	s_waitcnt vmcnt(1)
	ds_write_b128 v119, v[6:9] offset:17680
	s_waitcnt vmcnt(0)
	ds_write_b128 v119, v[10:13] offset:35088
	v_add_co_u32_e32 v10, vcc, s0, v16
	s_mov_b32 s0, 0x8000
	s_nop 0
	v_addc_co_u32_e32 v11, vcc, 0, v17, vcc
	global_load_dwordx4 v[2:5], v[10:11], off offset:1024
	global_load_dwordx4 v[6:9], v[10:11], off offset:2048
	s_nop 0
	global_load_dwordx4 v[10:13], v[10:11], off offset:3072
	s_waitcnt vmcnt(2)
	ds_write_b128 v119, v[2:5] offset:544
	s_waitcnt vmcnt(1)
	ds_write_b128 v119, v[6:9] offset:17952
	s_waitcnt vmcnt(0)
	ds_write_b128 v119, v[10:13] offset:35360
	v_add_co_u32_e32 v2, vcc, s0, v16
	s_mov_b32 s0, 0x9000
	s_nop 0
	v_addc_co_u32_e32 v3, vcc, 0, v17, vcc
	v_add_co_u32_e32 v10, vcc, s0, v16
	global_load_dwordx4 v[2:5], v[2:3], off offset:3072
	s_nop 0
	v_addc_co_u32_e32 v11, vcc, 0, v17, vcc
	global_load_dwordx4 v[6:9], v[10:11], off
	s_nop 0
	global_load_dwordx4 v[10:13], v[10:11], off offset:1024
	s_waitcnt vmcnt(2)
	ds_write_b128 v121, v[2:5]
	s_waitcnt vmcnt(1)
	ds_write_b128 v121, v[6:9] offset:17408
	s_waitcnt vmcnt(0)
	ds_write_b128 v121, v[10:13] offset:34816
	global_load_dword v1, v[114:115], off
	s_waitcnt vmcnt(0)
	ds_write_b32 v117, v1 offset:52224
	s_and_saveexec_b64 s[0:1], s[42:43]
	s_cbranch_execz .LBB0_154
	global_load_dword v1, v[114:115], off offset:1024
	s_waitcnt vmcnt(0)
	ds_write_b32 v117, v1 offset:53248

.LBB0_168:
	s_or_b64 exec, exec, s[4:5]
	s_movk_i32 s48, 0x110
	s_setprio 0
	s_branch .LBB0_172
